# code placement: uniform +40-byte shift of the whole kernel body (ten s_nop at entry)
# speedup vs baseline: 1.0036x; 1.0009x over previous
; #define LAS __attribute__((address_space(3)))
; __global__ void __launch_bounds__(NWAVES * 64, 2) hybrid_fwd(Args args) {
;     extern __shared__ __attribute__((aligned(16))) unsigned char lds_raw[];
;     LAS unsigned char* lds = (LAS unsigned char*)lds_raw;
;     volatile LAS unsigned* MISC = (volatile LAS unsigned*)(lds + MISC_OFF);
;     const int tid = threadIdx.x, wave = __builtin_amdgcn_readfirstlane(tid >> 6);
;     const int G = gridDim.x, bx = blockIdx.x;
;     const int vcu = (G % 8 == 0) ? (bx % 8) * (G / 8) + bx / 8 : bx;
_Z10hybrid_fwd4Args:
	s_nop 0
	s_nop 0
	s_nop 0
	s_nop 0
	s_nop 0
	s_nop 0
	s_nop 0
	s_nop 0
	s_nop 0
	s_nop 0
	s_load_dword s64, s[0:1], 0xd8
	v_readfirstlane_b32 s51, v0
	v_writelane_b32 v249, s2, 0
	s_mov_b32 s65, s2
	s_waitcnt lgkmcnt(0)
	s_and_b32 s4, s64, 7
	s_cmp_eq_u32 s4, 0
	s_cselect_b64 s[10:11], -1, 0
	s_cmp_lg_u32 s4, 0
	s_cbranch_scc1 .LBB0_2
	v_readlane_b32 s2, v249, 0
	s_ashr_i32 s5, s2, 31
	s_lshr_b32 s5, s5, 29
	s_add_i32 s5, s2, s5
	s_and_b32 s6, s5, -8
	s_ashr_i32 s4, s64, 3
	s_sub_i32 s6, s2, s6
	s_mul_i32 s4, s4, s6
	s_ashr_i32 s5, s5, 3
	s_add_i32 s65, s4, s5
